# mixer phase: static priority 1 for the wave in the odd slot of each SIMD
# baseline (speedup 1.0000x reference)
.LBB0_369:
	s_or_b64 exec, exec, s[0:1]
	v_readlane_b32 s8, v252, 2
	v_readlane_b32 s9, v252, 3
	s_mov_b64 s[8:9], 0x3e38aa3b
	v_readlane_b32 s10, v252, 4
	v_readlane_b32 s11, v252, 5
	v_readlane_b32 s14, v252, 8
	v_readlane_b32 s15, v252, 9
	s_lshl_b32 s0, s34, 4
	s_mov_b32 s1, s9
	s_mov_b64 s[14:15], s[10:11]
	s_lshl_b64 s[0:1], s[0:1], 2
	s_waitcnt lgkmcnt(0)
	s_barrier
	s_add_u32 s0, s14, s0
	s_addc_u32 s1, s15, s1
	s_add_u32 s0, s0, 0xf213640
	s_addc_u32 s1, s1, 0
	s_mov_b32 s10, s34
	v_writelane_b32 v253, s0, 49
	s_mov_b32 s11, s9
	v_readlane_b32 s12, v252, 6
	v_writelane_b32 v253, s1, 50
	s_lshl_b64 s[0:1], s[10:11], 2
	s_add_u32 s2, s14, s0
	s_addc_u32 s3, s15, s1
	s_add_u32 s0, s2, 0xf2136c0
	s_addc_u32 s1, s3, 0
	v_writelane_b32 v253, s0, 51
	v_readlane_b32 s13, v252, 7
	v_mov_b32_e32 v234, v250
	v_writelane_b32 v253, s1, 52
	s_nop 0
	v_readlane_b32 s0, v253, 25
	v_readlane_b32 s1, v253, 26
	s_and_b64 s[0:1], s[0:1], exec
	s_cselect_b32 s1, 0x80, 0
	s_cselect_b32 s0, 0xffffff80, 0
	s_or_b32 s8, s1, 0xc00
	v_writelane_b32 v253, s8, 53
	s_or_b32 s8, s1, 0x400
	v_writelane_b32 v253, s8, 54
	s_or_b32 s8, s1, 0x600
	v_writelane_b32 v253, s8, 55
	s_add_i32 s8, s0, 0xfffffa00
	v_writelane_b32 v253, s8, 56
	s_addk_i32 s0, 0xfc00
	v_writelane_b32 v253, s0, 57
	s_lshl_b32 s8, s34, 1
	s_lshl_b32 s79, s1, 8
	v_writelane_b32 v253, s8, 58
	s_lshl_b32 s8, s34, 11
	s_add_u32 s2, s2, 0xf213600
	s_addc_u32 s3, s3, 0
	v_writelane_b32 v253, s2, 59
	s_mul_i32 s0, s34, 0x18000
	s_mov_b32 s1, s9
	v_writelane_b32 v253, s3, 60
	s_add_u32 s2, s14, 0xb1d0000
	s_addc_u32 s3, s15, 0
	v_writelane_b32 v253, s2, 61
	s_nop 1
	v_writelane_b32 v253, s3, 62
	s_add_u32 s2, s14, 0xc9d0000
	s_addc_u32 s3, s15, 0
	v_writelane_b32 v253, s2, 63
	s_nop 1
	v_writelane_b32 v254, s3, 0
	s_add_u32 s2, s14, 0xbdd0000
	s_addc_u32 s3, s15, 0
	v_writelane_b32 v254, s2, 1
	s_nop 1
	v_writelane_b32 v254, s3, 2
	s_add_u32 s2, s14, 0x3dd0000
	s_addc_u32 s3, s15, 0
	v_writelane_b32 v254, s2, 3
	s_nop 1
	v_writelane_b32 v254, s3, 4
	s_add_u32 s2, s14, 0xd1d0000
	v_writelane_b32 v254, s2, 5
	s_addc_u32 s2, s15, 0
	v_writelane_b32 v254, s2, 6
	s_add_u32 s2, s14, 0xd1f0000
	v_writelane_b32 v254, s2, 7
	s_addc_u32 s2, s15, 0
	v_writelane_b32 v254, s2, 8
	s_add_u32 s2, s14, 0xd210000
	s_addc_u32 s3, s15, 0
	v_writelane_b32 v254, s2, 9
	s_nop 1
	v_writelane_b32 v254, s3, 10
	s_add_u32 s2, s14, 0xf00000
	v_writelane_b32 v254, s2, 11
	s_addc_u32 s2, s15, 0
	s_add_u32 s94, s14, 0x780000
	s_addc_u32 s95, s15, 0
	v_writelane_b32 v254, s2, 12
	s_add_u32 s2, s14, 0x1330000
	s_addc_u32 s3, s15, 0
	v_writelane_b32 v254, s2, 13
	s_nop 1
	v_writelane_b32 v254, s3, 14
	s_add_u32 s2, s14, 0x1380000
	s_addc_u32 s3, s15, 0
	s_add_u32 s20, s14, 0x15a0000
	s_addc_u32 s21, s15, 0
	s_add_u32 s96, s14, 0x16a0000
	v_writelane_b32 v254, s2, 15
	s_addc_u32 s97, s15, 0
	s_nop 0
	v_writelane_b32 v254, s3, 16
	s_add_u32 s2, s14, 0x17b0000
	s_addc_u32 s3, s15, 0
	v_writelane_b32 v254, s2, 17
	s_nop 1
	v_writelane_b32 v254, s3, 18
	s_add_u32 s2, s14, 0x17b8000
	s_addc_u32 s3, s15, 0
	v_writelane_b32 v254, s2, 19
	s_add_u32 s12, s14, 0x1bc0000
	s_addc_u32 s13, s15, 0
	v_writelane_b32 v254, s3, 20
	v_writelane_b32 v254, s12, 21
	s_nop 1
	v_writelane_b32 v254, s13, 22
	s_add_u32 s12, s14, 0x1cc0000
	s_addc_u32 s13, s15, 0
	v_writelane_b32 v254, s12, 23
	s_nop 1
	v_writelane_b32 v254, s13, 24
	s_add_u32 s12, s14, 0x3dd0a00
	s_addc_u32 s13, s15, 0
	s_lshl_b32 s10, s34, 17
	v_writelane_b32 v254, s12, 25
	s_add_u32 s10, s14, s10
	s_addc_u32 s11, s15, 0
	v_writelane_b32 v254, s13, 26
	s_mov_b32 s12, s34
	v_writelane_b32 v254, s12, 27
	s_add_u32 s10, s10, 0x1360000
	s_addc_u32 s11, s11, 0
	v_writelane_b32 v254, s13, 28
	v_writelane_b32 v254, s10, 29
	s_nop 1
	v_writelane_b32 v254, s11, 30
	s_add_u32 s10, s14, 0x3dd0800
	s_addc_u32 s11, s15, 0
	s_lshl_b64 s[0:1], s[0:1], 1
	s_add_u32 s0, s14, s0
	s_addc_u32 s1, s15, s1
	v_writelane_b32 v254, s10, 31
	s_add_u32 s0, s0, 0x1300000
	s_addc_u32 s1, s1, 0
	v_writelane_b32 v254, s11, 32
	v_writelane_b32 v254, s0, 33
	s_nop 1
	v_writelane_b32 v254, s1, 34
	s_add_u32 s0, s14, 0x13a0000
	v_writelane_b32 v254, s0, 35
	s_addc_u32 s0, s15, 0
	v_writelane_b32 v254, s0, 36
	s_mov_b64 s[0:1], 0
	v_writelane_b32 v254, s0, 37
	s_nop 1
	v_writelane_b32 v254, s1, 38
	s_lshl_b64 s[0:1], s[8:9], 2
	v_writelane_b32 v254, s0, 39
	s_nop 1
	v_writelane_b32 v254, s1, 40
	s_mov_b64 s[0:1], 0
	v_writelane_b32 v254, s0, 41
	s_nop 1
	v_writelane_b32 v254, s1, 42
	v_writelane_b32 v254, s14, 43
	s_nop 1
	v_writelane_b32 v254, s15, 44
	s_getreg_b32 s0, hwreg(HW_REG_HW_ID, 0, 1)
	s_cmp_eq_u32 s0, 0
	s_cbranch_scc1 .Lprio_skip
	s_setprio 1
.Lprio_skip:
	s_branch .LBB0_374
